# attention KV loop + scan step: packed f32 VALU ops split into scalar pairs
# baseline (speedup 1.0000x reference)
.LBB0_245:
	s_add_i32 s17, s13, s38
	s_addk_i32 s17, 0x7f
	s_cmp_le_i32 s17, s39
	s_cselect_b64 s[20:21], -1, 0
	v_cmp_eq_u32_e32 vcc, 0, v164
	s_and_b64 vcc, s[20:21], vcc
	s_nop 0
	v_cndmask_b32_e64 v176, 0, 1, vcc
	v_cmp_ne_u32_e64 s[20:21], 1, v176
	s_andn2_b64 vcc, exec, vcc
	s_cbranch_vccnz .LBB0_253
	s_cmp_lg_u32 s79, s38
	s_cbranch_scc1 .LBB0_248
	v_add_u32_e32 v163, s15, v194
	v_add_u32_e32 v164, 64, v163
	v_add_u32_e32 v165, 0x41, v163
	v_add_u32_e32 v166, 0x42, v163
	v_add_u32_e32 v167, 0x43, v163
	v_add_u32_e32 v168, 0x44, v163
	v_add_u32_e32 v169, 0x45, v163
	v_add_u32_e32 v170, 0x46, v163
	v_add_u32_e32 v171, 0x47, v163
	v_add_u32_e32 v172, 0x50, v163
	v_add_u32_e32 v173, 0x51, v163
	v_add_u32_e32 v174, 0x52, v163
	v_add_u32_e32 v175, 0x53, v163
	v_add_u32_e32 v176, 0x54, v163
	v_add_u32_e32 v177, 0x55, v163
	v_add_u32_e32 v178, 0x56, v163
	v_add_u32_e32 v179, 0x57, v163
	v_add_u32_e32 v180, 0x60, v163
	v_add_u32_e32 v181, 0x61, v163
	v_add_u32_e32 v182, 0x62, v163
	v_add_u32_e32 v183, 0x63, v163
	v_add_u32_e32 v184, 0x64, v163
	v_add_u32_e32 v185, 0x65, v163
	v_add_u32_e32 v200, 0x66, v163
	v_add_u32_e32 v201, 0x67, v163
	v_add_u32_e32 v202, 0x70, v163
	v_add_u32_e32 v203, 0x71, v163
	v_add_u32_e32 v204, 0x72, v163
	v_add_u32_e32 v205, 0x73, v163
	v_add_u32_e32 v206, 0x74, v163
	v_add_u32_e32 v207, 0x75, v163
	v_add_u32_e32 v208, 0x76, v163
	v_add_u32_e32 v163, 0x77, v163
	v_cvt_f32_i32_e32 v208, v208
	v_cvt_f32_i32_e32 v163, v163
	v_cvt_f32_i32_e32 v206, v206
	v_cvt_f32_i32_e32 v207, v207
	v_cvt_f32_i32_e32 v204, v204
	v_cvt_f32_i32_e32 v205, v205
	v_cvt_f32_i32_e32 v202, v202
	v_cvt_f32_i32_e32 v203, v203
	v_cvt_f32_i32_e32 v200, v200
	v_cvt_f32_i32_e32 v201, v201
	v_max_f32_e32 v208, 0, v208
	v_max_f32_e32 v209, 0, v163
	s_xor_b32 s19, s88, 0x80000000
	s_xor_b32 s18, s47, 0x80000000
	v_cvt_f32_i32_e32 v184, v184
	v_cvt_f32_i32_e32 v185, v185
	v_max_f32_e32 v206, 0, v206
	v_max_f32_e32 v207, 0, v207
	v_fma_f32 v78, s18, v208, v78
	v_fma_f32 v79, s19, v209, v79
	s_xor_b32 s19, s46, 0x80000000
	s_xor_b32 s18, s45, 0x80000000
	v_cvt_f32_i32_e32 v182, v182
	v_cvt_f32_i32_e32 v183, v183
	v_max_f32_e32 v204, 0, v204
	v_max_f32_e32 v205, 0, v205
	v_fma_f32 v76, s18, v206, v76
	v_fma_f32 v77, s19, v207, v77
	s_xor_b32 s19, s44, 0x80000000
	s_xor_b32 s18, s37, 0x80000000
	v_cvt_f32_i32_e32 v180, v180
	v_cvt_f32_i32_e32 v181, v181
	v_max_f32_e32 v202, 0, v202
	v_max_f32_e32 v203, 0, v203
	v_fma_f32 v74, s18, v204, v74
	v_fma_f32 v75, s19, v205, v75
	s_xor_b32 s19, s36, 0x80000000
	s_xor_b32 s18, s86, 0x80000000
	v_cvt_f32_i32_e32 v178, v178
	v_cvt_f32_i32_e32 v179, v179
	v_max_f32_e32 v200, 0, v200
	v_max_f32_e32 v201, 0, v201
	v_fma_f32 v72, s18, v202, v72
	v_fma_f32 v73, s19, v203, v73
	s_xor_b32 s19, s87, 0x80000000
	s_xor_b32 s18, s85, 0x80000000
	v_cvt_f32_i32_e32 v176, v176
	v_cvt_f32_i32_e32 v177, v177
	v_max_f32_e32 v184, 0, v184
	v_max_f32_e32 v185, 0, v185
	v_fma_f32 v70, s18, v200, v70
	v_fma_f32 v71, s19, v201, v71
	s_xor_b32 s19, s74, 0x80000000
	s_xor_b32 s18, s73, 0x80000000
	v_cvt_f32_i32_e32 v174, v174
	v_cvt_f32_i32_e32 v175, v175
	v_max_f32_e32 v182, 0, v182
	v_max_f32_e32 v183, 0, v183
	v_fma_f32 v68, s18, v184, v68
	v_fma_f32 v69, s19, v185, v69
	s_xor_b32 s19, s1, 0x80000000
	s_xor_b32 s18, s0, 0x80000000
	v_cvt_f32_i32_e32 v172, v172
	v_cvt_f32_i32_e32 v173, v173
	v_max_f32_e32 v180, 0, v180
	v_max_f32_e32 v181, 0, v181
	v_fma_f32 v66, s18, v182, v66
	v_fma_f32 v67, s19, v183, v67
	s_xor_b32 s19, s99, 0x80000000
	s_xor_b32 s18, s98, 0x80000000
	v_cvt_f32_i32_e32 v170, v170
	v_cvt_f32_i32_e32 v171, v171
	v_max_f32_e32 v178, 0, v178
	v_max_f32_e32 v179, 0, v179
	v_fma_f32 v64, s18, v180, v64
	v_fma_f32 v65, s19, v181, v65
	s_xor_b32 s19, s97, 0x80000000
	s_xor_b32 s18, s96, 0x80000000
	v_cvt_f32_i32_e32 v168, v168
	v_cvt_f32_i32_e32 v169, v169
	v_max_f32_e32 v176, 0, v176
	v_max_f32_e32 v177, 0, v177
	v_fma_f32 v94, s18, v178, v94
	v_fma_f32 v95, s19, v179, v95
	s_xor_b32 s19, s95, 0x80000000
	s_xor_b32 s18, s94, 0x80000000
	v_cvt_f32_i32_e32 v164, v164
	v_cvt_f32_i32_e32 v165, v165
	v_cvt_f32_i32_e32 v166, v166
	v_cvt_f32_i32_e32 v167, v167
	v_max_f32_e32 v174, 0, v174
	v_max_f32_e32 v175, 0, v175
	v_fma_f32 v92, s18, v176, v92
	v_fma_f32 v93, s19, v177, v93
	s_xor_b32 s19, s93, 0x80000000
	s_xor_b32 s18, s92, 0x80000000
	v_max_f32_e32 v172, 0, v172
	v_max_f32_e32 v173, 0, v173
	v_fma_f32 v90, s18, v174, v90
	v_fma_f32 v91, s19, v175, v91
	s_xor_b32 s19, s91, 0x80000000
	s_xor_b32 s18, s90, 0x80000000
	v_max_f32_e32 v170, 0, v170
	v_max_f32_e32 v171, 0, v171
	v_fma_f32 v88, s18, v172, v88
	v_fma_f32 v89, s19, v173, v89
	s_xor_b32 s19, s89, 0x80000000
	s_xor_b32 s18, s84, 0x80000000
	v_max_f32_e32 v168, 0, v168
	v_max_f32_e32 v169, 0, v169
	v_fma_f32 v86, s18, v170, v86
	v_fma_f32 v87, s19, v171, v87
	s_xor_b32 s19, s83, 0x80000000
	s_xor_b32 s18, s81, 0x80000000
	v_max_f32_e32 v164, 0, v164
	v_max_f32_e32 v165, 0, v165
	v_max_f32_e32 v166, 0, v166
	v_max_f32_e32 v167, 0, v167
	v_fma_f32 v84, s18, v168, v84
	v_fma_f32 v85, s19, v169, v85
	s_xor_b32 s19, s71, 0x80000000
	s_xor_b32 s18, s70, 0x80000000
	v_fma_f32 v82, s18, v166, v82
	v_fma_f32 v83, s19, v167, v83
	v_fma_f32 v80, -s68, v164, v80
	v_fma_f32 v81, -s69, v165, v81
.LBB0_248:
	v_max3_f32 v166, v80, v81, v82
	v_max3_f32 v167, v88, v89, v90
	v_max3_f32 v166, v166, v83, v84
	v_max3_f32 v167, v167, v91, v92
	v_max3_f32 v166, v166, v85, v86
	v_max3_f32 v167, v167, v93, v94
	v_max3_f32 v166, v166, v87, v95
	v_cvt_f32_i32_e32 v165, v155
	v_max3_f32 v168, v64, v65, v66
	v_max3_f32 v169, v72, v73, v74
	v_max3_f32 v168, v168, v67, v68
	v_max3_f32 v169, v169, v75, v76
	v_max3_f32 v168, v168, v69, v70
	v_max3_f32 v169, v169, v77, v78
	v_max3_f32 v168, v168, v71, v79
	v_max3_f32 v166, v166, v167, v169
	v_max_f32_e32 v163, v166, v168
	v_fma_f32 v163, -v161, v165, v163
	v_mov_b32_e32 v166, v163
	s_nop 1
	v_permlane32_swap_b32_e32 v166, v163
	v_max3_f32 v163, v162, v163, v166
	v_cmp_gt_f32_e32 vcc, v163, v162
	s_cbranch_vccz .LBB0_250
	v_sub_f32_e32 v162, v162, v163
	v_exp_f32_e32 v162, v162
	s_nop 0
	v_mul_f32_e32 v153, v153, v162
	v_mul_f32_e32 v62, v62, v162
	v_mul_f32_e32 v63, v63, v162
	v_mul_f32_e32 v60, v60, v162
	v_mul_f32_e32 v61, v61, v162
	v_mul_f32_e32 v58, v58, v162
	v_mul_f32_e32 v59, v59, v162
	v_mul_f32_e32 v56, v56, v162
	v_mul_f32_e32 v57, v57, v162
	v_mul_f32_e32 v54, v54, v162
	v_mul_f32_e32 v55, v55, v162
	v_mul_f32_e32 v52, v52, v162
	v_mul_f32_e32 v53, v53, v162
	v_mul_f32_e32 v50, v50, v162
	v_mul_f32_e32 v51, v51, v162
	v_mul_f32_e32 v48, v48, v162
	v_mul_f32_e32 v49, v49, v162
	v_mul_f32_e32 v46, v46, v162
	v_mul_f32_e32 v47, v47, v162
	v_mul_f32_e32 v44, v44, v162
	v_mul_f32_e32 v45, v45, v162
	v_mul_f32_e32 v42, v42, v162
	v_mul_f32_e32 v43, v43, v162
	v_mul_f32_e32 v40, v40, v162
	v_mul_f32_e32 v41, v41, v162
	v_mul_f32_e32 v38, v38, v162
	v_mul_f32_e32 v39, v39, v162
	v_mul_f32_e32 v36, v36, v162
	v_mul_f32_e32 v37, v37, v162
	v_mul_f32_e32 v34, v34, v162
	v_mul_f32_e32 v35, v35, v162
	v_mul_f32_e32 v32, v32, v162
	v_mul_f32_e32 v33, v33, v162
	v_mul_f32_e32 v30, v30, v162
	v_mul_f32_e32 v31, v31, v162
	v_mul_f32_e32 v28, v28, v162
	v_mul_f32_e32 v29, v29, v162
	v_mul_f32_e32 v26, v26, v162
	v_mul_f32_e32 v27, v27, v162
	v_mul_f32_e32 v24, v24, v162
	v_mul_f32_e32 v25, v25, v162
	v_mul_f32_e32 v22, v22, v162
	v_mul_f32_e32 v23, v23, v162
	v_mul_f32_e32 v20, v20, v162
	v_mul_f32_e32 v21, v21, v162
	v_mul_f32_e32 v18, v18, v162
	v_mul_f32_e32 v19, v19, v162
	v_mul_f32_e32 v16, v16, v162
	v_mul_f32_e32 v17, v17, v162
	v_mul_f32_e32 v14, v14, v162
	v_mul_f32_e32 v15, v15, v162
	v_mul_f32_e32 v12, v12, v162
	v_mul_f32_e32 v13, v13, v162
	v_mul_f32_e32 v10, v10, v162
	v_mul_f32_e32 v11, v11, v162
	v_mul_f32_e32 v8, v8, v162
	v_mul_f32_e32 v9, v9, v162
	v_mul_f32_e32 v6, v6, v162
	v_mul_f32_e32 v7, v7, v162
	v_mul_f32_e32 v4, v4, v162
	v_mul_f32_e32 v5, v5, v162
	v_mul_f32_e32 v2, v2, v162
	v_mul_f32_e32 v3, v3, v162
	v_mul_f32_e32 v0, v0, v162
	v_mul_f32_e32 v1, v1, v162
.LBB0_250:
	s_cmp_eq_u32 s75, s38
	v_mov_b32_e32 v164, 0
	s_cbranch_scc1 .LBB0_252
	v_add_u32_e32 v162, 1, v155
	v_cvt_f32_i32_e32 v211, v162
	s_waitcnt lgkmcnt(0)
	v_mul_f32_e32 v166, v160, v210
	v_mul_f32_e32 v167, v161, v211
	s_nop 0
	v_mov_b32_e32 v162, v166
	v_add_f32_e32 v168, s24, v162
	v_add_f32_e32 v169, s25, v163
	s_nop 0
	v_sub_f32_e32 v162, v168, v167
	v_cmp_lt_f32_e32 vcc, v162, v169
	s_cmp_eq_u64 vcc, exec
	s_cselect_b64 s[18:19], -1, 0
	v_cndmask_b32_e64 v164, 0, 1, s[18:19]

.LBB0_363:
	v_cvt_pk_bf16_f32 v48, v16, v17
	v_cvt_pk_bf16_f32 v49, v18, v19
	v_cvt_pk_bf16_f32 v50, v20, v21
	v_cvt_pk_bf16_f32 v51, v22, v23
	global_load_dwordx4 v[128:131], v[214:215], off offset:-4096
	global_load_dwordx4 v[124:127], v[214:215], off
	ds_read2_b64 v[32:35], v229 offset1:2
	ds_read2_b64 v[64:67], v229 offset0:4 offset1:6
	v_add_u32_e32 v235, 0x4000, v229
	s_waitcnt lgkmcnt(1)
	v_mfma_f32_32x32x16_bf16 v[32:47], v[48:51], v[32:35], 0
	ds_read2_b64 v[52:55], v235 offset0:32 offset1:34
	v_cvt_pk_bf16_f32 v68, v24, v25
	v_cvt_pk_bf16_f32 v69, v26, v27
	v_cvt_pk_bf16_f32 v70, v28, v29
	v_cvt_pk_bf16_f32 v71, v30, v31
	v_add_u32_e32 v236, s17, v219
	v_add_u32_e32 v237, 0x2080, v220
	s_waitcnt lgkmcnt(0)
	v_mfma_f32_32x32x16_bf16 v[48:63], v[48:51], v[52:55], 0
	v_add_u32_e32 v242, 0x20c8, v220
	v_add_u32_e32 v243, 0x20e0, v220
	v_add_u32_e32 v244, 0x20e8, v220
	v_mov_b32_e32 v175, v174
	v_mul_f32_e64 v30, v174, v30
	v_mul_f32_e64 v31, v175, v31
	v_mul_f32_e32 v28, v174, v28
	v_mul_f32_e32 v29, v175, v29
	v_mul_f32_e32 v26, v174, v26
	v_mul_f32_e32 v27, v175, v27
	v_mfma_f32_32x32x16_bf16 v[32:47], v[68:71], v[64:67], v[32:47]
	ds_read2_b64 v[64:67], v235 offset0:36 offset1:38
	v_mul_f32_e64 v24, v174, v24
	v_mul_f32_e64 v25, v175, v25
	v_mul_f32_e64 v22, v174, v22
	v_mul_f32_e64 v23, v175, v23
	v_mul_f32_e32 v20, v174, v20
	v_mul_f32_e32 v21, v175, v21
	v_mul_f32_e32 v18, v174, v18
	v_mul_f32_e32 v19, v175, v19
	v_mul_f32_e32 v16, v210, v16
	v_mul_f32_e32 v17, v211, v17
	s_add_i32 s44, s0, 2
	s_waitcnt lgkmcnt(0)
	v_mfma_f32_32x32x16_bf16 v[48:63], v[68:71], v[64:67], v[48:63]
	v_cvt_pk_bf16_f32 v64, v0, v1
	v_cvt_pk_bf16_f32 v65, v2, v3
	v_cvt_pk_bf16_f32 v66, v4, v5
	v_cvt_pk_bf16_f32 v67, v6, v7
	ds_read2_b64 v[68:71], v229 offset0:8 offset1:10
	v_mul_f32_e32 v6, v174, v6
	v_mul_f32_e32 v7, v175, v7
	v_mul_f32_e32 v4, v174, v4
	v_mul_f32_e32 v5, v175, v5
	s_waitcnt lgkmcnt(0)
	v_mfma_f32_32x32x16_bf16 v[32:47], v[64:67], v[68:71], v[32:47]
	ds_read2_b64 v[68:71], v235 offset0:40 offset1:42
	v_mul_f32_e64 v2, v174, v2
	v_mul_f32_e64 v3, v175, v3
	v_mul_f32_e64 v0, v210, v0
	v_mul_f32_e64 v1, v211, v1
	s_min_u32 s1, s44, 61
	s_mul_i32 s1, s1, 0xc0000
	s_add_i32 s4, s1, 0x180000
	s_add_i32 s0, s0, 3
	s_waitcnt lgkmcnt(0)
	v_mfma_f32_32x32x16_bf16 v[48:63], v[64:67], v[68:71], v[48:63]
	v_cvt_pk_bf16_f32 v64, v8, v9
	v_cvt_pk_bf16_f32 v65, v10, v11
	v_cvt_pk_bf16_f32 v66, v12, v13
	v_cvt_pk_bf16_f32 v67, v14, v15
	ds_read2_b64 v[68:71], v229 offset0:12 offset1:14
	v_mul_f32_e32 v14, v174, v14
	v_mul_f32_e32 v15, v175, v15
	v_mul_f32_e32 v12, v174, v12
	v_mul_f32_e32 v13, v175, v13
	s_waitcnt lgkmcnt(0)
	v_mfma_f32_32x32x16_bf16 v[32:47], v[64:67], v[68:71], v[32:47]
	ds_read2_b64 v[68:71], v235 offset0:44 offset1:46
	ds_read_b64_tr_b16 v[132:133], v219
	ds_read_b64_tr_b16 v[134:135], v219 offset:768
	ds_read_b64_tr_b16 v[136:137], v219 offset:3072
	ds_read_b64_tr_b16 v[138:139], v219 offset:3840
	ds_read_b64_tr_b16 v[140:141], v219 offset:6144
	ds_read_b64_tr_b16 v[142:143], v219 offset:6912
	ds_read_b64_tr_b16 v[144:145], v219 offset:9216
	ds_read_b64_tr_b16 v[146:147], v219 offset:9984
	ds_read_b64_tr_b16 v[238:239], v236
	ds_read_b64_tr_b16 v[240:241], v236 offset:768
	v_mul_f32_e32 v10, v174, v10
	v_mul_f32_e32 v11, v175, v11
	v_mul_f32_e32 v8, v174, v8
	v_mul_f32_e32 v9, v175, v9
	s_min_u32 s1, s0, 62
	s_min_u32 s0, s0, 61
	s_waitcnt lgkmcnt(10)
	v_mfma_f32_32x32x16_bf16 v[48:63], v[64:67], v[68:71], v[48:63]
	v_mul_f32_e64 v78, v194, v46
	v_mul_f32_e64 v79, v195, v47
	v_mul_f32_e64 v76, v192, v44
	v_mul_f32_e64 v77, v193, v45
	v_mul_f32_e64 v74, v190, v42
	v_mul_f32_e64 v75, v191, v43
	v_mul_f32_e32 v72, v188, v40
	v_mul_f32_e32 v73, v189, v41
	v_mul_f32_e32 v70, v186, v38
	v_mul_f32_e32 v71, v187, v39
	v_mul_f32_e32 v68, v184, v36
	v_mul_f32_e32 v69, v185, v37
	v_mul_f32_e32 v66, v182, v34
	v_mul_f32_e32 v67, v183, v35
	v_mul_f32_e32 v64, v172, v32
	v_mul_f32_e32 v65, v173, v33
	s_nop 0
	v_mul_f32_e32 v46, v208, v62
	v_mul_f32_e32 v47, v209, v63
	v_mul_f32_e32 v44, v206, v60
	v_mul_f32_e32 v45, v207, v61
	v_mul_f32_e32 v42, v204, v58
	v_mul_f32_e32 v43, v205, v59
	v_mul_f32_e32 v40, v202, v56
	v_mul_f32_e32 v41, v203, v57
	v_mul_f32_e32 v38, v200, v54
	v_mul_f32_e32 v39, v201, v55
	v_mul_f32_e32 v36, v198, v52
	v_mul_f32_e32 v37, v199, v53
	v_mul_f32_e32 v34, v196, v50
	v_mul_f32_e32 v35, v197, v51
	v_mul_f32_e32 v32, v180, v48
	v_mul_f32_e32 v33, v181, v49
	s_waitcnt vmcnt(12) lgkmcnt(0)
	v_mfma_f32_32x32x16_bf16 v[64:79], v[238:241], v[84:87], v[64:79]
	s_nop 11
	ds_write2_b32 v220, v64, v65 offset1:1
	ds_write2_b32 v220, v66, v67 offset0:2 offset1:3
	ds_write2_b32 v220, v68, v69 offset0:8 offset1:9
	ds_write2_b32 v220, v70, v71 offset0:10 offset1:11
	ds_write2_b32 v220, v72, v73 offset0:16 offset1:17
	ds_write2_b32 v220, v74, v75 offset0:18 offset1:19
	ds_write2_b32 v220, v76, v77 offset0:24 offset1:25
	ds_write2_b32 v220, v78, v79 offset0:26 offset1:27
	s_waitcnt vmcnt(11)
	v_mfma_f32_32x32x16_bf16 v[32:47], v[238:241], v[80:83], v[32:47]
	v_add_u32_e32 v238, 0x2088, v220
	v_add_u32_e32 v239, 0x20a0, v220
	v_add_u32_e32 v240, 0x20a8, v220
	v_add_u32_e32 v241, 0x20c0, v220
	s_mul_i32 s0, s0, 0xc0000
	v_lshl_add_u64 v[214:215], v[214:215], 0, s[12:13]
	s_nop 5
	ds_write2_b32 v237, v32, v33 offset1:1
	ds_write2_b32 v238, v34, v35 offset1:1
	ds_write2_b32 v239, v36, v37 offset1:1
	ds_write2_b32 v240, v38, v39 offset1:1
	ds_write2_b32 v241, v40, v41 offset1:1
	ds_write2_b32 v242, v42, v43 offset1:1
	ds_write2_b32 v243, v44, v45 offset1:1
	ds_write2_b32 v244, v46, v47 offset1:1
	ds_read_b64_tr_b16 v[32:33], v230 offset:33280
	ds_read_b64_tr_b16 v[34:35], v230 offset:35584
	s_waitcnt lgkmcnt(0)
	v_mfma_f32_32x32x16_bf16 v[16:31], v[32:35], v[132:135], v[16:31]
	ds_read_b64_tr_b16 v[32:33], v230 offset:42496
	ds_read_b64_tr_b16 v[34:35], v230 offset:44800
	s_waitcnt lgkmcnt(0)
	v_mfma_f32_32x32x16_bf16 v[16:31], v[32:35], v[136:139], v[16:31]
	ds_read_b64_tr_b16 v[32:33], v230 offset:51712
	ds_read_b64_tr_b16 v[34:35], v230 offset:54016
	s_waitcnt lgkmcnt(0)
	v_mfma_f32_32x32x16_bf16 v[16:31], v[32:35], v[140:143], v[16:31]
	ds_read_b64_tr_b16 v[32:33], v230 offset:60928
	ds_read_b64_tr_b16 v[34:35], v230 offset:63232
	s_waitcnt lgkmcnt(0)
	v_mfma_f32_32x32x16_bf16 v[16:31], v[32:35], v[144:147], v[16:31]
	ds_read_b64_tr_b16 v[32:33], v230 offset:33344
	ds_read_b64_tr_b16 v[34:35], v230 offset:35648
	s_waitcnt lgkmcnt(0)
	v_mfma_f32_32x32x16_bf16 v[0:15], v[32:35], v[132:135], v[0:15]
	ds_read_b64_tr_b16 v[32:33], v230 offset:42560
	ds_read_b64_tr_b16 v[34:35], v230 offset:44864
	v_add_u32_e32 v134, 0x4100, v223
	v_add_u32_e32 v135, 0x8200, v223
	v_lshl_add_u64 v[132:133], v[212:213], 0, s[14:15]
	s_waitcnt lgkmcnt(0)
	v_mfma_f32_32x32x16_bf16 v[0:15], v[32:35], v[136:139], v[0:15]
	ds_read_b64_tr_b16 v[32:33], v230 offset:51776
	ds_read_b64_tr_b16 v[34:35], v230 offset:54080
	v_add_u32_e32 v137, 0x4108, v223
	v_add_u32_e32 v136, 0xc300, v223
	v_add_u32_e32 v138, 0x8208, v223
	v_add_u32_e32 v139, 0xc308, v223
	s_waitcnt lgkmcnt(0)
	v_mfma_f32_32x32x16_bf16 v[0:15], v[32:35], v[140:143], v[0:15]
	ds_read_b64_tr_b16 v[32:33], v230 offset:60992
	ds_read_b64_tr_b16 v[34:35], v230 offset:63296
	s_waitcnt lgkmcnt(0)
	s_barrier
	v_add_u32_e32 v140, 0x4110, v223
	v_add_u32_e32 v143, 0x4118, v223
	v_add_u32_e32 v141, 0x8210, v223
	v_mfma_f32_32x32x16_bf16 v[0:15], v[32:35], v[144:147], v[0:15]
	v_add_u32_e32 v146, v154, v217
	v_add_u32_e32 v147, 0x2080, v146
	v_add_u32_e32 v245, 0x4100, v146
	v_lshl_add_u64 v[32:33], v[170:171], 0, s[4:5]
	s_waitcnt vmcnt(10)
	ds_write2_b64 v146, v[88:89], v[90:91] offset1:1
	s_waitcnt vmcnt(9)
	ds_write_b128 v231, v[92:95] offset:33280
	s_waitcnt vmcnt(8)
	ds_write2_b64 v147, v[96:97], v[98:99] offset1:1
	s_waitcnt vmcnt(7)
	ds_write_b128 v231, v[100:103] offset:42496
	s_waitcnt vmcnt(6)
	ds_write2_b64 v245, v[104:105], v[106:107] offset1:1
	s_waitcnt vmcnt(5)
	ds_write_b128 v231, v[108:111] offset:51712
	v_add_u32_e32 v108, 0x6180, v146
	v_add_co_u32_e32 v34, vcc, s21, v32
	s_waitcnt vmcnt(4)
	ds_write2_b64 v108, v[112:113], v[114:115] offset1:1
	s_waitcnt vmcnt(3)
	ds_write_b128 v231, v[116:119] offset:60928
	s_waitcnt vmcnt(2)
	ds_write_b128 v234, v[120:123]
	v_addc_co_u32_e32 v35, vcc, 0, v33, vcc
	global_load_dwordx4 v[64:67], v[32:33], off
	global_load_dwordx4 v[68:71], v[32:33], off offset:2048
	global_load_dwordx4 v[72:75], v[34:35], off
	global_load_dwordx4 v[76:79], v[34:35], off offset:2048
	v_add_co_u32_e32 v34, vcc, s24, v32
	v_add_u32_e32 v142, 0xc310, v223
	s_nop 0
	v_addc_co_u32_e32 v35, vcc, 0, v33, vcc
	v_add_co_u32_e32 v32, vcc, s25, v32
	global_load_dwordx4 v[88:91], v[34:35], off
	global_load_dwordx4 v[92:95], v[34:35], off offset:2048
	v_addc_co_u32_e32 v33, vcc, 0, v33, vcc
	global_load_dwordx4 v[96:99], v[32:33], off
	global_load_dwordx4 v[100:103], v[32:33], off offset:2048
	v_lshl_add_u64 v[32:33], v[176:177], 0, s[4:5]
	global_load_dwordx4 v[104:107], v[32:33], off
	ds_read2_b32 v[32:33], v223 offset1:1
	ds_read2_b32 v[34:35], v134 offset1:1
	ds_read2_b32 v[36:37], v137 offset1:1
	ds_read2_b32 v[38:39], v140 offset1:1
	ds_read2_b32 v[40:41], v143 offset1:1
	s_waitcnt lgkmcnt(4)
	v_add_f32_e32 v32, 0, v32
	v_add_f32_e32 v33, 0, v33
	v_add_u32_e32 v144, 0x8218, v223
	s_waitcnt lgkmcnt(3)
	v_add_f32_e32 v32, v32, v34
	v_add_f32_e32 v33, v33, v35
	ds_read2_b32 v[34:35], v135 offset1:1
	v_add_u32_e32 v145, 0xc318, v223
	s_lshl_b32 s4, s1, 13
	v_cvt_pk_bf16_f32 v114, v24, v25
	v_cvt_pk_bf16_f32 v115, v26, v27
	s_waitcnt lgkmcnt(0)
	v_add_f32_e32 v32, v32, v34
	v_add_f32_e32 v33, v33, v35
	ds_read2_b32 v[34:35], v136 offset1:1
	v_cvt_pk_bf16_f32 v116, v28, v29
	v_cvt_pk_bf16_f32 v117, v30, v31
	v_mul_f32_e32 v30, v174, v30
	v_mul_f32_e32 v31, v175, v31
	v_mul_f32_e32 v28, v174, v28
	v_mul_f32_e32 v29, v175, v29
	s_waitcnt lgkmcnt(0)
	v_add_f32_e32 v32, v32, v34
	v_add_f32_e32 v33, v33, v35
	ds_read2_b32 v[34:35], v224 offset1:1
	v_cvt_pk_bf16_f32 v32, v32, v33
	v_mul_f32_e32 v26, v174, v26
	v_mul_f32_e32 v27, v175, v27
	v_mul_f32_e32 v24, v174, v24
	v_mul_f32_e32 v25, v175, v25
	s_waitcnt lgkmcnt(0)
	v_add_f32_e32 v34, 0, v34
	v_add_f32_e32 v35, 0, v35
	s_nop 0
	v_add_f32_e32 v34, v34, v36
	v_add_f32_e32 v35, v35, v37
	ds_read2_b32 v[36:37], v138 offset1:1
	s_waitcnt lgkmcnt(0)
	v_add_f32_e32 v34, v34, v36
	v_add_f32_e32 v35, v35, v37
	ds_read2_b32 v[36:37], v139 offset1:1
	s_waitcnt lgkmcnt(0)
	v_add_f32_e32 v34, v34, v36
	v_add_f32_e32 v35, v35, v37
	ds_read2_b32 v[36:37], v225 offset1:1
	v_cvt_pk_bf16_f32 v33, v34, v35
	s_waitcnt lgkmcnt(0)
	v_add_f32_e32 v36, 0, v36
	v_add_f32_e32 v37, 0, v37
	s_nop 0
	v_add_f32_e32 v36, v36, v38
	v_add_f32_e32 v37, v37, v39
	ds_read2_b32 v[38:39], v141 offset1:1
	s_waitcnt lgkmcnt(0)
	v_add_f32_e32 v36, v36, v38
	v_add_f32_e32 v37, v37, v39
	ds_read2_b32 v[38:39], v142 offset1:1
	s_waitcnt lgkmcnt(0)
	v_add_f32_e32 v36, v36, v38
	v_add_f32_e32 v37, v37, v39
	ds_read2_b32 v[38:39], v226 offset1:1
	v_cvt_pk_bf16_f32 v34, v36, v37
	v_add_co_u32_e32 v36, vcc, s27, v132
	s_waitcnt lgkmcnt(0)
	v_add_f32_e32 v38, 0, v38
	v_add_f32_e32 v39, 0, v39
	s_nop 0
	v_add_f32_e32 v38, v38, v40
	v_add_f32_e32 v39, v39, v41
	ds_read2_b32 v[40:41], v144 offset1:1
	v_addc_co_u32_e32 v37, vcc, 0, v133, vcc
	s_waitcnt lgkmcnt(0)
	v_add_f32_e32 v38, v38, v40
	v_add_f32_e32 v39, v39, v41
	ds_read2_b32 v[40:41], v145 offset1:1
	s_waitcnt lgkmcnt(0)
	v_add_f32_e32 v38, v38, v40
	v_add_f32_e32 v39, v39, v41
	s_nop 0
	v_cvt_pk_bf16_f32 v35, v38, v39
	global_store_dwordx4 v[36:37], v[32:35], off
	s_barrier
	s_nop 0
	v_lshl_add_u64 v[32:33], v[178:179], 0, s[4:5]
	v_add_co_u32_e32 v32, vcc, s16, v32
	s_nop 1
	v_addc_co_u32_e32 v33, vcc, 0, v33, vcc
	global_load_dwordx4 v[84:87], v[32:33], off offset:-4096
	global_load_dwordx4 v[80:83], v[32:33], off
	v_cvt_pk_bf16_f32 v32, v16, v17
	v_cvt_pk_bf16_f32 v33, v18, v19
	v_cvt_pk_bf16_f32 v34, v20, v21
	v_cvt_pk_bf16_f32 v35, v22, v23
	ds_read2_b64 v[36:39], v229 offset1:2
	ds_read2_b64 v[110:113], v229 offset0:4 offset1:6
	s_waitcnt lgkmcnt(1)
	v_mfma_f32_32x32x16_bf16 v[48:63], v[32:35], v[36:39], 0
	ds_read2_b64 v[36:39], v235 offset0:32 offset1:34
	v_mul_f32_e64 v22, v174, v22
	v_mul_f32_e64 v23, v175, v23
	v_mul_f32_e64 v20, v174, v20
	v_mul_f32_e64 v21, v175, v21
	v_mul_f32_e32 v18, v174, v18
	v_mul_f32_e32 v19, v175, v19
	v_mul_f32_e32 v16, v210, v16
	v_mul_f32_e32 v17, v211, v17
	s_add_i32 s4, s0, 0x180000
	s_add_u32 s14, s14, 0x180000
	s_waitcnt lgkmcnt(0)
	v_mfma_f32_32x32x16_bf16 v[32:47], v[32:35], v[36:39], 0
	s_addc_u32 s15, s15, 0
	s_cmp_gt_u32 s44, 61
	s_mov_b32 s0, s44
	v_mfma_f32_32x32x16_bf16 v[48:63], v[114:117], v[110:113], v[48:63]
	ds_read2_b64 v[110:113], v235 offset0:36 offset1:38
	s_waitcnt lgkmcnt(0)
	v_mfma_f32_32x32x16_bf16 v[32:47], v[114:117], v[110:113], v[32:47]
	v_cvt_pk_bf16_f32 v110, v0, v1
	v_cvt_pk_bf16_f32 v111, v2, v3
	v_cvt_pk_bf16_f32 v112, v4, v5
	v_cvt_pk_bf16_f32 v113, v6, v7
	ds_read2_b64 v[114:117], v229 offset0:8 offset1:10
	v_mul_f32_e32 v6, v174, v6
	v_mul_f32_e32 v7, v175, v7
	v_mul_f32_e32 v4, v174, v4
	v_mul_f32_e32 v5, v175, v5
	s_waitcnt lgkmcnt(0)
	v_mfma_f32_32x32x16_bf16 v[48:63], v[110:113], v[114:117], v[48:63]
	ds_read2_b64 v[114:117], v235 offset0:40 offset1:42
	v_mul_f32_e64 v2, v174, v2
	v_mul_f32_e64 v3, v175, v3
	v_mul_f32_e64 v0, v210, v0
	v_mul_f32_e64 v1, v211, v1
	s_waitcnt lgkmcnt(0)
	v_mfma_f32_32x32x16_bf16 v[32:47], v[110:113], v[114:117], v[32:47]
	v_cvt_pk_bf16_f32 v110, v8, v9
	v_cvt_pk_bf16_f32 v111, v10, v11
	v_cvt_pk_bf16_f32 v112, v12, v13
	v_cvt_pk_bf16_f32 v113, v14, v15
	ds_read2_b64 v[114:117], v229 offset0:12 offset1:14
	v_mul_f32_e32 v14, v174, v14
	v_mul_f32_e32 v15, v175, v15
	v_mul_f32_e32 v12, v174, v12
	v_mul_f32_e32 v13, v175, v13
	s_waitcnt lgkmcnt(0)
	v_mfma_f32_32x32x16_bf16 v[48:63], v[110:113], v[114:117], v[48:63]
	ds_read2_b64 v[114:117], v235 offset0:44 offset1:46
	v_mul_f32_e64 v10, v174, v10
	v_mul_f32_e64 v11, v175, v11
	v_mul_f32_e64 v8, v174, v8
	v_mul_f32_e64 v9, v175, v9
	s_nop 6
	v_mul_f32_e32 v62, v194, v62
	v_mul_f32_e32 v63, v195, v63
	s_waitcnt lgkmcnt(0)
	v_mfma_f32_32x32x16_bf16 v[32:47], v[110:113], v[114:117], v[32:47]
	ds_read_b64_tr_b16 v[110:111], v219
	ds_read_b64_tr_b16 v[112:113], v219 offset:768
	ds_read_b64_tr_b16 v[114:115], v219 offset:3072
	ds_read_b64_tr_b16 v[116:117], v219 offset:3840
	ds_read_b64_tr_b16 v[118:119], v219 offset:6144
	ds_read_b64_tr_b16 v[120:121], v219 offset:6912
	ds_read_b64_tr_b16 v[246:247], v219 offset:9216
	ds_read_b64_tr_b16 v[248:249], v219 offset:9984
	ds_read_b64_tr_b16 v[250:251], v236
	ds_read_b64_tr_b16 v[252:253], v236 offset:768
	v_mul_f32_e32 v60, v192, v60
	v_mul_f32_e32 v61, v193, v61
	v_mul_f32_e32 v58, v190, v58
	v_mul_f32_e32 v59, v191, v59
	v_mul_f32_e32 v56, v188, v56
	v_mul_f32_e32 v57, v189, v57
	v_mul_f32_e32 v54, v186, v54
	v_mul_f32_e32 v55, v187, v55
	v_mul_f32_e32 v52, v184, v52
	v_mul_f32_e32 v53, v185, v53
	v_mul_f32_e32 v50, v182, v50
	v_mul_f32_e32 v51, v183, v51
	v_mul_f32_e32 v48, v172, v48
	v_mul_f32_e32 v49, v173, v49
	v_mul_f32_e32 v46, v208, v46
	v_mul_f32_e32 v47, v209, v47
	v_mul_f32_e32 v44, v206, v44
	v_mul_f32_e32 v45, v207, v45
	s_waitcnt vmcnt(13) lgkmcnt(0)
	v_mfma_f32_32x32x16_bf16 v[48:63], v[250:253], v[128:131], v[48:63]
	v_mul_f32_e64 v42, v204, v42
	v_mul_f32_e64 v43, v205, v43
	v_mul_f32_e64 v40, v202, v40
	v_mul_f32_e64 v41, v203, v41
	v_mul_f32_e64 v38, v200, v38
	v_mul_f32_e64 v39, v201, v39
	v_mul_f32_e32 v36, v198, v36
	v_mul_f32_e32 v37, v199, v37
	v_mul_f32_e32 v34, v196, v34
	v_mul_f32_e32 v35, v197, v35
	v_mul_f32_e32 v32, v180, v32
	v_mul_f32_e32 v33, v181, v33
	s_waitcnt vmcnt(12)
	s_nop 0
	v_mfma_f32_32x32x16_bf16 v[32:47], v[250:253], v[124:127], v[32:47]
	ds_write2_b32 v220, v48, v49 offset1:1
	ds_write2_b32 v220, v50, v51 offset0:2 offset1:3
	ds_write2_b32 v220, v52, v53 offset0:8 offset1:9
	ds_write2_b32 v220, v54, v55 offset0:10 offset1:11
	ds_write2_b32 v220, v56, v57 offset0:16 offset1:17
	ds_write2_b32 v220, v58, v59 offset0:18 offset1:19
	ds_write2_b32 v220, v60, v61 offset0:24 offset1:25
	ds_write2_b32 v220, v62, v63 offset0:26 offset1:27
	s_nop 3
	ds_write2_b32 v237, v32, v33 offset1:1
	ds_write2_b32 v238, v34, v35 offset1:1
	ds_write2_b32 v239, v36, v37 offset1:1
	ds_write2_b32 v240, v38, v39 offset1:1
	ds_write2_b32 v241, v40, v41 offset1:1
	ds_write2_b32 v242, v42, v43 offset1:1
	ds_write2_b32 v243, v44, v45 offset1:1
	ds_write2_b32 v244, v46, v47 offset1:1
	ds_read_b64_tr_b16 v[32:33], v230 offset:33280
	ds_read_b64_tr_b16 v[34:35], v230 offset:35584
	s_waitcnt lgkmcnt(0)
	v_mfma_f32_32x32x16_bf16 v[16:31], v[32:35], v[110:113], v[16:31]
	ds_read_b64_tr_b16 v[32:33], v230 offset:42496
	ds_read_b64_tr_b16 v[34:35], v230 offset:44800
	s_waitcnt lgkmcnt(0)
	v_mfma_f32_32x32x16_bf16 v[16:31], v[32:35], v[114:117], v[16:31]
	ds_read_b64_tr_b16 v[32:33], v230 offset:51712
	ds_read_b64_tr_b16 v[34:35], v230 offset:54016
	s_waitcnt lgkmcnt(0)
	v_mfma_f32_32x32x16_bf16 v[16:31], v[32:35], v[118:121], v[16:31]
	ds_read_b64_tr_b16 v[32:33], v230 offset:60928
	ds_read_b64_tr_b16 v[34:35], v230 offset:63232
	s_waitcnt lgkmcnt(0)
	v_mfma_f32_32x32x16_bf16 v[16:31], v[32:35], v[246:249], v[16:31]
	ds_read_b64_tr_b16 v[32:33], v230 offset:33344
	ds_read_b64_tr_b16 v[34:35], v230 offset:35648
	s_waitcnt lgkmcnt(0)
	v_mfma_f32_32x32x16_bf16 v[0:15], v[32:35], v[110:113], v[0:15]
	ds_read_b64_tr_b16 v[32:33], v230 offset:42560
	ds_read_b64_tr_b16 v[34:35], v230 offset:44864
	s_waitcnt lgkmcnt(0)
	v_mfma_f32_32x32x16_bf16 v[0:15], v[32:35], v[114:117], v[0:15]
	ds_read_b64_tr_b16 v[32:33], v230 offset:51776
	ds_read_b64_tr_b16 v[34:35], v230 offset:54080
	s_waitcnt lgkmcnt(0)
	v_mfma_f32_32x32x16_bf16 v[0:15], v[32:35], v[118:121], v[0:15]
	ds_read_b64_tr_b16 v[32:33], v230 offset:60992
	ds_read_b64_tr_b16 v[34:35], v230 offset:63296
	s_waitcnt lgkmcnt(0)
	s_barrier
	s_waitcnt vmcnt(11)
	ds_write2_b64 v146, v[64:65], v[66:67] offset1:1
	s_waitcnt vmcnt(10)
	ds_write_b128 v231, v[68:71] offset:33280
	s_waitcnt vmcnt(9)
	ds_write2_b64 v147, v[72:73], v[74:75] offset1:1
	s_waitcnt vmcnt(8)
	ds_write_b128 v231, v[76:79] offset:42496
	s_waitcnt vmcnt(7)
	ds_write2_b64 v245, v[88:89], v[90:91] offset1:1
	s_waitcnt vmcnt(6)
	ds_write_b128 v231, v[92:95] offset:51712
	s_waitcnt vmcnt(5)
	ds_write2_b64 v108, v[96:97], v[98:99] offset1:1
	s_waitcnt vmcnt(4)
	ds_write_b128 v231, v[100:103] offset:60928
	s_waitcnt vmcnt(3)
	ds_write_b128 v234, v[104:107]
	v_mfma_f32_32x32x16_bf16 v[0:15], v[32:35], v[246:249], v[0:15]
	v_lshl_add_u64 v[32:33], v[170:171], 0, s[4:5]
	v_add_co_u32_e32 v34, vcc, s21, v32
	global_load_dwordx4 v[88:91], v[32:33], off
	global_load_dwordx4 v[92:95], v[32:33], off offset:2048
	v_addc_co_u32_e32 v35, vcc, 0, v33, vcc
	global_load_dwordx4 v[96:99], v[34:35], off
	global_load_dwordx4 v[100:103], v[34:35], off offset:2048
	v_add_co_u32_e32 v34, vcc, s24, v32
	s_nop 1
	v_addc_co_u32_e32 v35, vcc, 0, v33, vcc
	v_add_co_u32_e32 v32, vcc, s25, v32
	global_load_dwordx4 v[104:107], v[34:35], off
	global_load_dwordx4 v[108:111], v[34:35], off offset:2048
	v_addc_co_u32_e32 v33, vcc, 0, v33, vcc
	global_load_dwordx4 v[112:115], v[32:33], off
	global_load_dwordx4 v[116:119], v[32:33], off offset:2048
	v_lshl_add_u64 v[32:33], v[176:177], 0, s[4:5]
	global_load_dwordx4 v[120:123], v[32:33], off
	ds_read2_b32 v[32:33], v223 offset1:1
	ds_read2_b32 v[34:35], v134 offset1:1
	ds_read2_b32 v[36:37], v137 offset1:1
	ds_read2_b32 v[38:39], v140 offset1:1
	ds_read2_b32 v[40:41], v143 offset1:1
	s_waitcnt lgkmcnt(4)
	v_add_f32_e32 v32, 0, v32
	v_add_f32_e32 v33, 0, v33
	s_waitcnt lgkmcnt(3)
	v_add_f32_e32 v32, v32, v34
	v_add_f32_e32 v33, v33, v35
	ds_read2_b32 v[34:35], v135 offset1:1
	s_waitcnt lgkmcnt(0)
	v_add_f32_e32 v32, v32, v34
	v_add_f32_e32 v33, v33, v35
	ds_read2_b32 v[34:35], v136 offset1:1
	s_waitcnt lgkmcnt(0)
	v_add_f32_e32 v32, v32, v34
	v_add_f32_e32 v33, v33, v35
	ds_read2_b32 v[34:35], v224 offset1:1
	v_cvt_pk_bf16_f32 v32, v32, v33
	s_waitcnt lgkmcnt(0)
	v_add_f32_e32 v34, 0, v34
	v_add_f32_e32 v35, 0, v35
	s_nop 0
	v_add_f32_e32 v34, v34, v36
	v_add_f32_e32 v35, v35, v37
	ds_read2_b32 v[36:37], v138 offset1:1
	s_waitcnt lgkmcnt(0)
	v_add_f32_e32 v34, v34, v36
	v_add_f32_e32 v35, v35, v37
	ds_read2_b32 v[36:37], v139 offset1:1
	s_waitcnt lgkmcnt(0)
	v_add_f32_e32 v34, v34, v36
	v_add_f32_e32 v35, v35, v37
	ds_read2_b32 v[36:37], v225 offset1:1
	v_cvt_pk_bf16_f32 v33, v34, v35
	s_waitcnt lgkmcnt(0)
	v_add_f32_e32 v36, 0, v36
	v_add_f32_e32 v37, 0, v37
	s_nop 0
	v_add_f32_e32 v36, v36, v38
	v_add_f32_e32 v37, v37, v39
	ds_read2_b32 v[38:39], v141 offset1:1
	s_waitcnt lgkmcnt(0)
	v_add_f32_e32 v36, v36, v38
	v_add_f32_e32 v37, v37, v39
	ds_read2_b32 v[38:39], v142 offset1:1
	s_waitcnt lgkmcnt(0)
	v_add_f32_e32 v36, v36, v38
	v_add_f32_e32 v37, v37, v39
	ds_read2_b32 v[38:39], v226 offset1:1
	v_cvt_pk_bf16_f32 v34, v36, v37
	v_add_co_u32_e32 v36, vcc, s40, v132
	s_waitcnt lgkmcnt(0)
	v_add_f32_e32 v38, 0, v38
	v_add_f32_e32 v39, 0, v39
	s_nop 0
	v_add_f32_e32 v38, v38, v40
	v_add_f32_e32 v39, v39, v41
	ds_read2_b32 v[40:41], v144 offset1:1
	v_addc_co_u32_e32 v37, vcc, 0, v133, vcc
	s_waitcnt lgkmcnt(0)
	v_add_f32_e32 v38, v38, v40
	v_add_f32_e32 v39, v39, v41
	ds_read2_b32 v[40:41], v145 offset1:1
	s_waitcnt lgkmcnt(0)
	v_add_f32_e32 v38, v38, v40
	v_add_f32_e32 v39, v39, v41
	s_nop 0
	v_cvt_pk_bf16_f32 v35, v38, v39
	global_store_dwordx4 v[36:37], v[32:35], off
	s_barrier
	s_cbranch_scc0 .LBB0_363
	s_cmpk_lt_u32 s41, 0x80
	s_cbranch_scc0 .LBB0_361
	v_lshl_or_b32 v32, s42, 9, v156
	v_or_b32_e32 v32, s43, v32
	v_lshlrev_b32_e32 v32, 9, v32
	v_mov_b32_e32 v33, v151
	v_lshl_add_u64 v[32:33], v[158:159], 0, v[32:33]
	v_cvt_pk_bf16_f32 v16, v16, v17
	v_cvt_pk_bf16_f32 v17, v18, v19
	v_cvt_pk_bf16_f32 v0, v0, v1
	v_cvt_pk_bf16_f32 v1, v2, v3
	global_store_dwordx2 v[32:33], v[16:17], off
	v_cvt_pk_bf16_f32 v16, v20, v21
	v_cvt_pk_bf16_f32 v17, v22, v23
	global_store_dwordx2 v[32:33], v[0:1], off offset:64
	v_cvt_pk_bf16_f32 v0, v4, v5
	v_cvt_pk_bf16_f32 v1, v6, v7
	global_store_dwordx2 v[32:33], v[16:17], off offset:16
	v_cvt_pk_bf16_f32 v16, v24, v25
	v_cvt_pk_bf16_f32 v17, v26, v27
	global_store_dwordx2 v[32:33], v[0:1], off offset:80
	v_cvt_pk_bf16_f32 v0, v8, v9
	v_cvt_pk_bf16_f32 v1, v10, v11
	global_store_dwordx2 v[32:33], v[16:17], off offset:32
	v_cvt_pk_bf16_f32 v16, v28, v29
	v_cvt_pk_bf16_f32 v17, v30, v31
	global_store_dwordx2 v[32:33], v[0:1], off offset:96
	v_cvt_pk_bf16_f32 v0, v12, v13
	v_cvt_pk_bf16_f32 v1, v14, v15
	global_store_dwordx2 v[32:33], v[16:17], off offset:48
	global_store_dwordx2 v[32:33], v[0:1], off offset:112
	s_branch .LBB0_361
